# mixer phase: 132 of 256 workgroups start on the paged sample attention (2 units each), the others never join that queue
# speedup vs baseline: 1.0029x; 1.0029x over previous
.LBB0_1582:
	v_readlane_b32 s0, v255, 12
	v_readlane_b32 s1, v255, 13
	s_cmp_lt_i32 s0, 7
	s_cselect_b64 s[0:1], -1, 0
	s_and_b64 s[18:19], s[0:1], s[2:3]
	s_andn2_b64 vcc, exec, s[18:19]
	s_cbranch_vccnz .LBB0_2069
	s_and_b32 s37, s87, 0xffffffc0
	s_waitcnt vmcnt(0)
	v_mbcnt_lo_u32_b32 v0, -1, 0
	v_mbcnt_hi_u32_b32 v0, -1, v0
	s_mov_b32 s22, 0
	v_add_u32_e32 v0, s37, v0
	s_ashr_i32 s23, s22, 31
	v_readlane_b32 s0, v255, 4
	v_readlane_b32 s1, v255, 5
	s_add_u32 s20, s0, s22
	s_addc_u32 s21, s1, s23
	s_sub_i32 s0, s73, 0x84
	s_cmp_lt_i32 s33, s0
	v_readlane_b32 s0, v255, 9
	v_readlane_b32 s1, v255, 10
	s_mov_b32 s1, 0
	v_writelane_b32 v255, s0, 9
	s_nop 1
	v_writelane_b32 v255, s1, 10
	s_cbranch_scc1 .LBB0_1624
	v_mbcnt_lo_u32_b32 v0, -1, 0
	v_mbcnt_hi_u32_b32 v0, -1, v0
	v_readlane_b32 s0, v255, 14
	v_add_u32_e32 v0, s37, v0
	s_cmp_lt_u32 s0, 64
	v_readlane_b32 s30, v255, 9
	s_cselect_b64 s[0:1], -1, 0
	s_add_i32 s2, s30, 1
	v_and_b32_e32 v176, 63, v0
	v_cvt_f32_u32_e32 v0, s2
	s_mov_b32 s3, 0x42fc0000
	v_mov_b32_e32 v1, 0x42800000
	s_lshl_b32 s2, s30, 14
	v_cmp_lt_f32_e32 vcc, s3, v0
	s_add_i32 s39, s2, 0
	s_and_b64 s[2:3], vcc, exec
	v_cndmask_b32_e32 v1, 0, v1, vcc
	v_sub_f32_e32 v0, v1, v0
	v_exp_f32_e32 v0, v0
	s_cselect_b32 s2, 0xffffffc0, 0
	v_readlane_b32 s31, v255, 10
	v_readlane_b32 s6, v255, 2
	v_ldexp_f32 v0, v0, s2
	s_lshl_b32 s2, s30, 8
	s_add_u32 s4, s20, s2
	s_addc_u32 s5, s21, 0
	s_add_u32 s8, s4, 0x47000000
	s_addc_u32 s9, s5, 0
	s_lshl_b64 s[10:11], s[30:31], 7
	s_lshl_b64 s[2:3], s[22:23], 3
	v_readlane_b32 s7, v255, 3
	s_add_u32 s12, s6, s2
	s_addc_u32 s13, s7, s3
	s_add_u32 s14, s20, 0x61800000
	s_addc_u32 s15, s21, 0
	s_add_u32 s16, s20, 0x61900000
	s_addc_u32 s17, s21, 0
	s_add_u32 s24, s20, 0x61a00000
	s_addc_u32 s25, s21, 0
	s_add_u32 s26, s4, 0x48100000
	s_addc_u32 s27, s5, 0
	s_add_u32 s28, s4, 0x49200000
	v_mul_f32_e32 v177, 0x3fb8aa3b, v0
	s_addc_u32 s29, s5, 0
	v_cndmask_b32_e64 v0, 0, 1, s[0:1]
	s_add_i32 s46, 0, 0x23f40
	s_movk_i32 s44, 0x2000
	s_add_i32 s45, s39, 0x2000
	s_lshl_b64 s[30:31], s[30:31], 9
	v_cmp_ne_u32_e64 s[2:3], 1, v0
	v_mov_b32_e32 v137, 0
	v_mov_b32_e32 v178, s46
	s_movk_i32 s47, 0x110
	s_movk_i32 s49, 0x4000
	s_movk_i32 s56, 0x6000
	s_mov_b32 s57, 0x8000
	s_mov_b32 s58, 0xa000
	s_mov_b32 s59, 0xc000
	s_mov_b32 s60, 0xe000
	s_mov_b32 s61, 0x10000
	s_mov_b32 s62, 0x12000
	s_mov_b32 s63, 0x14000
	s_mov_b32 s64, 0x16000
	s_mov_b32 s65, 0x18000
	s_mov_b32 s66, 0x1a000
	s_mov_b32 s67, 0x1c000
	s_mov_b32 s68, 0x1e000
	s_mov_b32 s69, 0x64000
	s_mov_b32 s70, 0x66000
	s_mov_b32 s71, 0x68000
	s_mov_b32 s72, 0x6a000
	s_mov_b32 s74, 0x6c000
	s_mov_b32 s76, 0x6e000
	s_mov_b32 s77, 0x70000
	s_mov_b32 s78, 0x72000
	s_mov_b32 s79, 0x74000
	s_mov_b32 s80, 0x76000
	s_mov_b32 s81, 0x78000
	s_mov_b32 s82, 0x7a000
	s_mov_b32 s83, 0x7c000
	s_mov_b32 s84, 0x7e000
	s_movk_i32 s85, 0x210
	s_movk_i32 s86, 0x1000
	s_mov_b32 s87, 0x61a00000
	v_mov_b32_e32 v179, 0xf149f2ca
	s_branch .LBB0_1588
